# importance pass: next head's Q fragments prefetched into spare registers while the current head is computed
# baseline (speedup 1.0000x reference)
.LBB0_569:
	v_writelane_b32 v243, s24, 53
	v_lshrrev_b32_e32 v3, 1, v192
	v_readlane_b32 s20, v243, 21
	v_readlane_b32 s21, v243, 22
	v_readlane_b32 s22, v243, 23
	v_readlane_b32 s23, v243, 24
	s_mov_b32 s21, s20
	s_mov_b32 s22, s20
	s_mov_b32 s23, s20
	v_mov_b64_e32 v[4:5], s[20:21]
	v_mov_b64_e32 v[6:7], s[22:23]
	ds_write_b128 v193, v[4:7]
	ds_write_b128 v193, v[4:7] offset:1024
	ds_write_b128 v193, v[4:7] offset:2048
	ds_write_b128 v193, v[4:7] offset:3072
	ds_write_b128 v193, v[4:7] offset:4096
	ds_write_b128 v193, v[4:7] offset:5120
	ds_write_b128 v193, v[4:7] offset:6144
	ds_write_b128 v193, v[4:7] offset:7168
	v_bfe_u32 v4, v192, 1, 3
	v_bitop3_b32 v5, v85, v3, 7 bitop3:0x78
	v_lshlrev_b32_e32 v8, 4, v5
	v_bitop3_b32 v5, v85, v4, 2 bitop3:0x36
	v_lshlrev_b32_e32 v6, 2, v85
	v_lshlrev_b32_e32 v9, 4, v5
	v_bitop3_b32 v5, v85, v4, 4 bitop3:0x36
	v_bitop3_b32 v4, v85, v4, 6 bitop3:0x36
	s_sub_i32 s0, s33, 31
	v_lshlrev_b32_e32 v11, 4, v4
	v_sub_u32_e32 v4, v195, v6
	s_ashr_i32 s14, s0, 4
	v_cmp_gt_i32_e64 s[0:1], 0, v4
	s_ashr_i32 s12, s33, 9
	s_cmp_gt_i32 s12, -1
	v_writelane_b32 v243, s0, 54
	s_cselect_b64 s[80:81], -1, 0
	s_cmp_lt_i32 s14, 31
	v_writelane_b32 v243, s1, 55
	v_cmp_gt_i32_e64 s[0:1], 1, v4
	s_cselect_b64 s[82:83], -1, 0
	s_cmp_gt_i32 s12, 0
	v_writelane_b32 v243, s0, 56
	s_cselect_b64 s[84:85], -1, 0
	s_cmp_lt_i32 s14, 63
	v_writelane_b32 v243, s1, 57
	v_cmp_gt_i32_e64 s[0:1], 2, v4
	s_cselect_b64 s[86:87], -1, 0
	s_cmp_gt_i32 s12, 1
	v_writelane_b32 v243, s0, 58
	s_cselect_b64 s[88:89], -1, 0
	s_cmpk_lt_i32 s14, 0x5f
	v_writelane_b32 v243, s1, 59
	v_cmp_gt_i32_e64 s[0:1], 3, v4
	s_cselect_b64 s[90:91], -1, 0
	s_cmp_gt_i32 s12, 2
	v_writelane_b32 v243, s0, 60
	s_cselect_b64 s[92:93], -1, 0
	s_cmpk_lt_i32 s14, 0x7f
	v_writelane_b32 v243, s1, 61
	v_cmp_gt_i32_e64 s[0:1], 8, v4
	s_cselect_b64 s[94:95], -1, 0
	s_cmp_gt_i32 s12, 3
	v_writelane_b32 v243, s0, 62
	s_cselect_b64 s[96:97], -1, 0
	s_cmpk_lt_i32 s14, 0x9f
	v_writelane_b32 v243, s1, 63
	v_cmp_gt_i32_e64 s[0:1], 9, v4
	s_cselect_b64 s[98:99], -1, 0
	s_cmp_gt_i32 s12, 4
	v_writelane_b32 v242, s0, 0
	s_cselect_b64 s[78:79], -1, 0
	s_cmpk_lt_i32 s14, 0xbf
	v_writelane_b32 v242, s1, 1
	v_cmp_gt_i32_e64 s[0:1], 10, v4
	s_cselect_b64 s[8:9], -1, 0
	s_cmp_gt_i32 s12, 5
	v_writelane_b32 v242, s0, 2
	s_mov_b32 s24, s20
	v_lshlrev_b32_e32 v10, 4, v5
	v_writelane_b32 v242, s1, 3
	v_cmp_gt_i32_e64 s[0:1], 11, v4
	s_mov_b32 s17, s20
	v_or_b32_e32 v16, 0xa0, v6
	v_writelane_b32 v242, s0, 4
	v_sub_u32_e32 v34, v195, v16
	v_or_b32_e32 v16, 0xc0, v6
	v_writelane_b32 v242, s1, 5
	v_cmp_gt_i32_e64 s[0:1], 16, v4
	v_sub_u32_e32 v35, v195, v16
	v_or_b32_e32 v13, 64, v6
	v_writelane_b32 v242, s0, 6
	v_sub_u32_e32 v13, v195, v13
	v_or_b32_e32 v14, 0x60, v6
	v_writelane_b32 v242, s1, 7
	v_cmp_gt_i32_e64 s[0:1], 17, v4
	v_sub_u32_e32 v14, v195, v14
	v_or_b32_e32 v15, 0x80, v6
	v_writelane_b32 v242, s0, 8
	v_sub_u32_e32 v15, v195, v15
	s_waitcnt vmcnt(0)
	v_lshl_add_u32 v7, v86, 7, 0
	v_writelane_b32 v242, s1, 9
	v_cmp_gt_i32_e64 s[0:1], 18, v4
	s_waitcnt vmcnt(0)
	v_mov_b32_e32 v19, v18
	v_mov_b32_e32 v20, v18
	v_writelane_b32 v242, s0, 10
	v_mov_b32_e32 v21, v18
	v_mov_b32_e32 v22, v18
	v_writelane_b32 v242, s1, 11
	v_cmp_gt_i32_e64 s[0:1], 19, v4
	v_mov_b32_e32 v23, v18
	v_mov_b32_e32 v24, v18
	v_writelane_b32 v242, s0, 12
	v_mov_b32_e32 v25, v18
	v_mov_b32_e32 v26, v18
	v_writelane_b32 v242, s1, 13
	v_cmp_gt_i32_e64 s[0:1], 24, v4
	v_mov_b32_e32 v27, v18
	v_mov_b32_e32 v28, v18
	v_writelane_b32 v242, s0, 14
	v_mov_b32_e32 v29, v18
	v_mov_b32_e32 v30, v18
	v_writelane_b32 v242, s1, 15
	v_cmp_gt_i32_e64 s[0:1], 25, v4
	v_mov_b32_e32 v31, v18
	v_mov_b32_e32 v32, v18
	v_writelane_b32 v242, s0, 16
	v_mov_b32_e32 v33, v18
	v_cmp_lt_u32_e64 s[6:7], 31, v84
	v_writelane_b32 v242, s1, 17
	v_cmp_gt_i32_e64 s[0:1], 26, v4
	v_add_u32_e32 v88, v7, v8
	v_add_u32_e32 v89, v7, v9
	v_writelane_b32 v242, s0, 18
	v_add_u32_e32 v90, v7, v10
	v_add_u32_e32 v91, v7, v11
	v_writelane_b32 v242, s1, 19
	v_cmp_gt_i32_e64 s[0:1], 27, v4
	v_or_b32_e32 v4, 32, v6
	v_sub_u32_e32 v12, v195, v4
	v_writelane_b32 v242, s0, 20
	v_or_b32_e32 v6, 0xe0, v6
	v_sub_u32_e32 v6, v195, v6
	v_writelane_b32 v242, s1, 21
	v_cmp_gt_i32_e64 s[0:1], 0, v12
	v_cmp_gt_i32_e64 s[18:19], 3, v35
	v_cmp_gt_i32_e64 s[20:21], 8, v35
	v_writelane_b32 v242, s0, 22
	v_cmp_gt_i32_e64 s[22:23], 9, v35
	v_cmp_gt_i32_e64 s[28:29], 16, v35
	v_writelane_b32 v242, s1, 23
	v_cmp_gt_i32_e64 s[0:1], 1, v12
	v_cmp_gt_i32_e64 s[30:31], 17, v35
	v_cmp_gt_i32_e64 s[34:35], 18, v35
	v_writelane_b32 v242, s0, 24
	v_cmp_gt_i32_e64 s[36:37], 19, v35
	v_cmp_gt_i32_e64 s[38:39], 24, v35
	v_writelane_b32 v242, s1, 25
	v_cmp_gt_i32_e64 s[0:1], 2, v12
	v_cmp_gt_i32_e64 s[40:41], 25, v35
	v_cmp_gt_i32_e64 s[42:43], 26, v35
	v_writelane_b32 v242, s0, 26
	v_cmp_gt_i32_e64 s[44:45], 27, v35
	v_cmp_gt_i32_e64 s[46:47], 0, v6
	v_writelane_b32 v242, s1, 27
	v_cmp_gt_i32_e64 s[0:1], 3, v12
	v_cmp_gt_i32_e64 s[48:49], 1, v6
	v_cmp_gt_i32_e64 s[50:51], 2, v6
	v_writelane_b32 v242, s0, 28
	v_cmp_gt_i32_e64 s[52:53], 3, v6
	v_cmp_gt_i32_e64 s[54:55], 8, v6
	v_writelane_b32 v242, s1, 29
	v_cmp_gt_i32_e64 s[0:1], 8, v12
	v_cmp_gt_i32_e64 s[56:57], 9, v6
	v_cmp_gt_i32_e64 s[58:59], 10, v6
	v_writelane_b32 v242, s0, 30
	v_cmp_gt_i32_e64 s[60:61], 11, v6
	v_cmp_gt_i32_e64 s[62:63], 16, v6
	v_writelane_b32 v242, s1, 31
	v_cmp_gt_i32_e64 s[0:1], 9, v12
	v_cmp_gt_i32_e64 s[64:65], 17, v6
	v_cmp_gt_i32_e64 s[66:67], 18, v6
	v_writelane_b32 v242, s0, 32
	v_cmp_gt_i32_e64 s[68:69], 19, v6
	v_cmp_gt_i32_e64 s[70:71], 24, v6
	v_writelane_b32 v242, s1, 33
	v_cmp_gt_i32_e64 s[0:1], 10, v12
	v_cmp_gt_i32_e64 s[72:73], 25, v6
	v_cmp_gt_i32_e64 s[74:75], 26, v6
	v_writelane_b32 v242, s0, 34
	v_cmp_gt_i32_e64 s[76:77], 27, v6
	s_waitcnt lgkmcnt(0)
	v_writelane_b32 v242, s1, 35
	v_cmp_gt_i32_e64 s[0:1], 11, v12
	s_barrier
	s_nop 0
	v_writelane_b32 v242, s0, 36
	s_nop 1
	v_writelane_b32 v242, s1, 37
	v_cmp_gt_i32_e64 s[0:1], 16, v12
	s_nop 1
	v_writelane_b32 v242, s0, 38
	s_nop 1
	v_writelane_b32 v242, s1, 39
	s_cselect_b64 s[0:1], -1, 0
	s_cmpk_lt_i32 s14, 0xdf
	s_cselect_b64 s[10:11], -1, 0
	s_cmp_gt_i32 s12, 6
	s_cselect_b64 s[12:13], -1, 0
	s_cmpk_lt_i32 s14, 0xff
	s_cselect_b64 s[14:15], -1, 0
	s_add_i32 s16, s33, s27
	v_writelane_b32 v242, s27, 40
	v_add_u32_e32 v4, s16, v86
	v_writelane_b32 v242, s26, 41
	s_lshl_b32 s16, s26, 25
	v_writelane_b32 v243, s24, 21
	v_ashrrev_i32_e32 v5, 31, v4
	v_lshlrev_b64 v[4:5], 7, v[4:5]
	v_writelane_b32 v243, s25, 22
	v_writelane_b32 v243, s26, 23
	v_lshl_add_u64 v[4:5], s[16:17], 0, v[4:5]
	v_cmp_gt_i32_e64 s[16:17], 17, v12
	v_writelane_b32 v243, s27, 24
	v_and_or_b32 v4, v3, 16, v4
	v_writelane_b32 v242, s16, 42
	v_cmp_gt_i32_e64 s[24:25], 10, v35
	v_cmp_gt_i32_e64 s[26:27], 11, v35
	v_writelane_b32 v242, s17, 43
	v_readlane_b32 s16, v243, 19
	v_readlane_b32 s17, v243, 20
	s_nop 1
	v_lshl_add_u64 v[16:17], s[16:17], 0, v[4:5]
	v_cmp_gt_i32_e64 s[16:17], 18, v12
	s_nop 1
	v_writelane_b32 v242, s16, 44
	s_nop 1
	v_writelane_b32 v242, s17, 45
	v_cmp_gt_i32_e64 s[16:17], 19, v12
	s_nop 1
	v_writelane_b32 v242, s16, 46
	s_nop 1
	v_writelane_b32 v242, s17, 47
	v_cmp_gt_i32_e64 s[16:17], 24, v12
	s_nop 1
	v_writelane_b32 v242, s16, 48
	s_nop 1
	v_writelane_b32 v242, s17, 49
	v_cmp_gt_i32_e64 s[16:17], 25, v12
	s_nop 1
	v_writelane_b32 v242, s16, 50
	s_nop 1
	v_writelane_b32 v242, s17, 51
	v_cmp_gt_i32_e64 s[16:17], 26, v12
	s_nop 1
	v_writelane_b32 v242, s16, 52
	s_nop 1
	v_writelane_b32 v242, s17, 53
	v_cmp_gt_i32_e64 s[16:17], 27, v12
	s_nop 1
	v_writelane_b32 v242, s16, 54
	s_nop 1
	v_writelane_b32 v242, s17, 55
	v_cmp_gt_i32_e64 s[16:17], 0, v13
	s_nop 1
	v_writelane_b32 v242, s16, 56
	s_nop 1
	v_writelane_b32 v242, s17, 57
	v_cmp_gt_i32_e64 s[16:17], 1, v13
	s_nop 1
	v_writelane_b32 v242, s16, 58
	s_nop 1
	v_writelane_b32 v242, s17, 59
	v_cmp_gt_i32_e64 s[16:17], 2, v13
	s_nop 1
	v_writelane_b32 v242, s16, 60
	s_nop 1
	v_writelane_b32 v242, s17, 61
	v_cmp_gt_i32_e64 s[16:17], 3, v13
	s_nop 1
	v_writelane_b32 v242, s16, 62
	s_nop 1
	v_writelane_b32 v242, s17, 63
	v_cmp_gt_i32_e64 s[16:17], 8, v13
	s_nop 1
	v_writelane_b32 v241, s16, 0
	s_nop 1
	v_writelane_b32 v241, s17, 1
	v_cmp_gt_i32_e64 s[16:17], 9, v13
	s_nop 1
	v_writelane_b32 v241, s16, 2
	s_nop 1
	v_writelane_b32 v241, s17, 3
	v_cmp_gt_i32_e64 s[16:17], 10, v13
	s_nop 1
	v_writelane_b32 v241, s16, 4
	s_nop 1
	v_writelane_b32 v241, s17, 5
	v_cmp_gt_i32_e64 s[16:17], 11, v13
	s_nop 1
	v_writelane_b32 v241, s16, 6
	s_nop 1
	v_writelane_b32 v241, s17, 7
	v_cmp_gt_i32_e64 s[16:17], 16, v13
	s_nop 1
	v_writelane_b32 v241, s16, 8
	s_nop 1
	v_writelane_b32 v241, s17, 9
	v_cmp_gt_i32_e64 s[16:17], 17, v13
	s_nop 1
	v_writelane_b32 v241, s16, 10
	s_nop 1
	v_writelane_b32 v241, s17, 11
	v_cmp_gt_i32_e64 s[16:17], 18, v13
	s_nop 1
	v_writelane_b32 v241, s16, 12
	s_nop 1
	v_writelane_b32 v241, s17, 13
	v_cmp_gt_i32_e64 s[16:17], 19, v13
	s_nop 1
	v_writelane_b32 v241, s16, 14
	s_nop 1
	v_writelane_b32 v241, s17, 15
	v_cmp_gt_i32_e64 s[16:17], 24, v13
	s_nop 1
	v_writelane_b32 v241, s16, 16
	s_nop 1
	v_writelane_b32 v241, s17, 17
	v_cmp_gt_i32_e64 s[16:17], 25, v13
	s_nop 1
	v_writelane_b32 v241, s16, 18
	s_nop 1
	v_writelane_b32 v241, s17, 19
	v_cmp_gt_i32_e64 s[16:17], 26, v13
	s_nop 1
	v_writelane_b32 v241, s16, 20
	s_nop 1
	v_writelane_b32 v241, s17, 21
	v_cmp_gt_i32_e64 s[16:17], 27, v13
	s_nop 1
	v_writelane_b32 v241, s16, 22
	s_nop 1
	v_writelane_b32 v241, s17, 23
	v_cmp_gt_i32_e64 s[16:17], 0, v14
	s_nop 1
	v_writelane_b32 v241, s16, 24
	s_nop 1
	v_writelane_b32 v241, s17, 25
	v_cmp_gt_i32_e64 s[16:17], 1, v14
	s_nop 1
	v_writelane_b32 v241, s16, 26
	s_nop 1
	v_writelane_b32 v241, s17, 27
	v_cmp_gt_i32_e64 s[16:17], 2, v14
	s_nop 1
	v_writelane_b32 v241, s16, 28
	s_nop 1
	v_writelane_b32 v241, s17, 29
	v_cmp_gt_i32_e64 s[16:17], 3, v14
	s_nop 1
	v_writelane_b32 v241, s16, 30
	s_nop 1
	v_writelane_b32 v241, s17, 31
	v_cmp_gt_i32_e64 s[16:17], 8, v14
	s_nop 1
	v_writelane_b32 v241, s16, 32
	s_nop 1
	v_writelane_b32 v241, s17, 33
	v_cmp_gt_i32_e64 s[16:17], 9, v14
	s_nop 1
	v_writelane_b32 v241, s16, 34
	s_nop 1
	v_writelane_b32 v241, s17, 35
	v_cmp_gt_i32_e64 s[16:17], 10, v14
	s_nop 1
	v_writelane_b32 v241, s16, 36
	s_nop 1
	v_writelane_b32 v241, s17, 37
	v_cmp_gt_i32_e64 s[16:17], 11, v14
	s_nop 1
	v_writelane_b32 v241, s16, 38
	s_nop 1
	v_writelane_b32 v241, s17, 39
	v_cmp_gt_i32_e64 s[16:17], 16, v14
	s_nop 1
	v_writelane_b32 v241, s16, 40
	s_nop 1
	v_writelane_b32 v241, s17, 41
	v_cmp_gt_i32_e64 s[16:17], 17, v14
	s_nop 1
	v_writelane_b32 v241, s16, 42
	s_nop 1
	v_writelane_b32 v241, s17, 43
	v_cmp_gt_i32_e64 s[16:17], 18, v14
	s_nop 1
	v_writelane_b32 v241, s16, 44
	s_nop 1
	v_writelane_b32 v241, s17, 45
	v_cmp_gt_i32_e64 s[16:17], 19, v14
	s_nop 1
	v_writelane_b32 v241, s16, 46
	s_nop 1
	v_writelane_b32 v241, s17, 47
	v_cmp_gt_i32_e64 s[16:17], 24, v14
	s_nop 1
	v_writelane_b32 v241, s16, 48
	s_nop 1
	v_writelane_b32 v241, s17, 49
	v_cmp_gt_i32_e64 s[16:17], 25, v14
	s_nop 1
	v_writelane_b32 v241, s16, 50
	s_nop 1
	v_writelane_b32 v241, s17, 51
	v_cmp_gt_i32_e64 s[16:17], 26, v14
	s_nop 1
	v_writelane_b32 v241, s16, 52
	s_nop 1
	v_writelane_b32 v241, s17, 53
	v_cmp_gt_i32_e64 s[16:17], 27, v14
	s_nop 1
	v_writelane_b32 v241, s16, 54
	s_nop 1
	v_writelane_b32 v241, s17, 55
	v_cmp_gt_i32_e64 s[16:17], 0, v15
	s_nop 1
	v_writelane_b32 v241, s16, 56
	s_nop 1
	v_writelane_b32 v241, s17, 57
	v_cmp_gt_i32_e64 s[16:17], 1, v15
	s_nop 1
	v_writelane_b32 v241, s16, 58
	s_nop 1
	v_writelane_b32 v241, s17, 59
	v_cmp_gt_i32_e64 s[16:17], 2, v15
	s_nop 1
	v_writelane_b32 v241, s16, 60
	s_nop 1
	v_writelane_b32 v241, s17, 61
	v_cmp_gt_i32_e64 s[16:17], 3, v15
	s_nop 1
	v_writelane_b32 v241, s16, 62
	s_nop 1
	v_writelane_b32 v241, s17, 63
	v_cmp_gt_i32_e64 s[16:17], 8, v15
	s_nop 1
	v_writelane_b32 v240, s16, 0
	s_nop 1
	v_writelane_b32 v240, s17, 1
	v_cmp_gt_i32_e64 s[16:17], 9, v15
	s_nop 1
	v_writelane_b32 v240, s16, 2
	s_nop 1
	v_writelane_b32 v240, s17, 3
	v_cmp_gt_i32_e64 s[16:17], 10, v15
	s_nop 1
	v_writelane_b32 v240, s16, 4
	s_nop 1
	v_writelane_b32 v240, s17, 5
	v_cmp_gt_i32_e64 s[16:17], 11, v15
	s_nop 1
	v_writelane_b32 v240, s16, 6
	s_nop 1
	v_writelane_b32 v240, s17, 7
	v_cmp_gt_i32_e64 s[16:17], 16, v15
	s_nop 1
	v_writelane_b32 v240, s16, 8
	s_nop 1
	v_writelane_b32 v240, s17, 9
	v_cmp_gt_i32_e64 s[16:17], 17, v15
	s_nop 1
	v_writelane_b32 v240, s16, 10
	s_nop 1
	v_writelane_b32 v240, s17, 11
	v_cmp_gt_i32_e64 s[16:17], 18, v15
	s_nop 1
	v_writelane_b32 v240, s16, 12
	s_nop 1
	v_writelane_b32 v240, s17, 13
	v_cmp_gt_i32_e64 s[16:17], 19, v15
	s_nop 1
	v_writelane_b32 v240, s16, 14
	s_nop 1
	v_writelane_b32 v240, s17, 15
	v_cmp_gt_i32_e64 s[16:17], 24, v15
	s_nop 1
	v_writelane_b32 v240, s16, 16
	s_nop 1
	v_writelane_b32 v240, s17, 17
	v_cmp_gt_i32_e64 s[16:17], 25, v15
	s_nop 1
	v_writelane_b32 v240, s16, 18
	s_nop 1
	v_writelane_b32 v240, s17, 19
	v_cmp_gt_i32_e64 s[16:17], 26, v15
	s_nop 1
	v_writelane_b32 v240, s16, 20
	s_nop 1
	v_writelane_b32 v240, s17, 21
	v_cmp_gt_i32_e64 s[16:17], 27, v15
	s_nop 1
	v_writelane_b32 v240, s16, 22
	s_nop 1
	v_writelane_b32 v240, s17, 23
	v_cmp_gt_i32_e64 s[16:17], 0, v34
	s_nop 1
	v_writelane_b32 v240, s16, 24
	s_nop 1
	v_writelane_b32 v240, s17, 25
	v_cmp_gt_i32_e64 s[16:17], 1, v34
	s_nop 1
	v_writelane_b32 v240, s16, 26
	s_nop 1
	v_writelane_b32 v240, s17, 27
	v_cmp_gt_i32_e64 s[16:17], 2, v34
	s_nop 1
	v_writelane_b32 v240, s16, 28
	s_nop 1
	v_writelane_b32 v240, s17, 29
	v_cmp_gt_i32_e64 s[16:17], 3, v34
	s_nop 1
	v_writelane_b32 v240, s16, 30
	s_nop 1
	v_writelane_b32 v240, s17, 31
	v_cmp_gt_i32_e64 s[16:17], 8, v34
	s_nop 1
	v_writelane_b32 v240, s16, 32
	s_nop 1
	v_writelane_b32 v240, s17, 33
	v_cmp_gt_i32_e64 s[16:17], 9, v34
	s_nop 1
	v_writelane_b32 v240, s16, 34
	s_nop 1
	v_writelane_b32 v240, s17, 35
	v_cmp_gt_i32_e64 s[16:17], 10, v34
	s_nop 1
	v_writelane_b32 v240, s16, 36
	s_nop 1
	v_writelane_b32 v240, s17, 37
	v_cmp_gt_i32_e64 s[16:17], 11, v34
	s_nop 1
	v_writelane_b32 v240, s16, 38
	s_nop 1
	v_writelane_b32 v240, s17, 39
	v_cmp_gt_i32_e64 s[16:17], 16, v34
	s_nop 1
	v_writelane_b32 v240, s16, 40
	s_nop 1
	v_writelane_b32 v240, s17, 41
	v_cmp_gt_i32_e64 s[16:17], 17, v34
	s_nop 1
	v_writelane_b32 v240, s16, 42
	s_nop 1
	v_writelane_b32 v240, s17, 43
	v_cmp_gt_i32_e64 s[16:17], 18, v34
	s_nop 1
	v_writelane_b32 v240, s16, 44
	s_nop 1
	v_writelane_b32 v240, s17, 45
	v_cmp_gt_i32_e64 s[16:17], 19, v34
	s_nop 1
	v_writelane_b32 v240, s16, 46
	s_nop 1
	v_writelane_b32 v240, s17, 47
	v_cmp_gt_i32_e64 s[16:17], 24, v34
	s_nop 1
	v_writelane_b32 v240, s16, 48
	s_nop 1
	v_writelane_b32 v240, s17, 49
	v_cmp_gt_i32_e64 s[16:17], 25, v34
	s_nop 1
	v_writelane_b32 v240, s16, 50
	s_nop 1
	v_writelane_b32 v240, s17, 51
	v_cmp_gt_i32_e64 s[16:17], 26, v34
	s_nop 1
	v_writelane_b32 v240, s16, 52
	s_nop 1
	v_writelane_b32 v240, s17, 53
	v_cmp_gt_i32_e64 s[16:17], 27, v34
	s_nop 1
	v_writelane_b32 v240, s16, 54
	s_nop 1
	v_writelane_b32 v240, s17, 55
	v_cmp_gt_i32_e64 s[16:17], 0, v35
	s_nop 1
	v_writelane_b32 v240, s16, 56
	s_nop 1
	v_writelane_b32 v240, s17, 57
	v_cmp_gt_i32_e64 s[16:17], 1, v35
	s_nop 1
	v_writelane_b32 v240, s16, 58
	s_nop 1
	v_writelane_b32 v240, s17, 59
	v_cmp_gt_i32_e64 s[16:17], 2, v35
	s_nop 1
	v_writelane_b32 v240, s16, 60
	s_nop 1
	v_writelane_b32 v240, s17, 61
	s_mov_b64 s[16:17], 0
	global_load_dwordx4 v[214:217], v[16:17], off offset:-64
	global_load_dwordx4 v[218:221], v[16:17], off offset:-32
	global_load_dwordx4 v[222:225], v[16:17], off
	global_load_dwordx4 v[226:229], v[16:17], off offset:32
	s_branch .LBB0_572

.LBB0_571:
	s_nop 0
	v_mov_b32_e32 v4, v81
	s_add_u32 s16, s16, 0x800000
	s_nop 0
	v_permlane32_swap_b32_e32 v81, v4
	v_add_f32_e32 v8, v81, v4
	v_div_scale_f32 v4, vcc, v8, v8, 1.0
	v_rcp_f32_e32 v5, v4
	v_mov_b32_e32 v81, v3
	s_addc_u32 s17, s17, 0
	s_cmp_lg_u32 s16, 0x2000000
	v_fma_f32 v6, -v4, v5, 1.0
	v_fmac_f32_e32 v5, v6, v5
	v_div_scale_f32 v6, vcc, 1.0, v8, 1.0
	v_mul_f32_e32 v7, v6, v5
	v_fma_f32 v9, -v4, v7, v6
	v_fmac_f32_e32 v7, v9, v5
	v_fma_f32 v4, -v4, v7, v6
	v_div_fmas_f32 v9, v4, v5, v7
	ds_read_b128 v[4:7], v193
	v_div_fixup_f32 v9, v9, v8, 1.0
	v_cmp_lt_f32_e32 vcc, 0, v8
	s_nop 1
	v_cndmask_b32_e32 v12, 0, v9, vcc
	ds_read_b128 v[8:11], v193 offset:1024
	s_waitcnt lgkmcnt(1)
	v_pk_fma_f32 v[6:7], v[58:59], v[12:13], v[6:7] op_sel_hi:[1,0,1]
	v_pk_fma_f32 v[4:5], v[54:55], v[12:13], v[4:5] op_sel_hi:[1,0,1]
	ds_write_b128 v193, v[4:7]
	ds_read_b128 v[4:7], v193 offset:2048
	s_waitcnt lgkmcnt(2)
	v_pk_fma_f32 v[10:11], v[60:61], v[12:13], v[10:11] op_sel_hi:[1,0,1]
	v_pk_fma_f32 v[8:9], v[56:57], v[12:13], v[8:9] op_sel_hi:[1,0,1]
	ds_write_b128 v193, v[8:11] offset:1024
	ds_read_b128 v[8:11], v193 offset:3072
	s_waitcnt lgkmcnt(2)
	v_pk_fma_f32 v[6:7], v[64:65], v[12:13], v[6:7] op_sel_hi:[1,0,1]
	v_pk_fma_f32 v[4:5], v[62:63], v[12:13], v[4:5] op_sel_hi:[1,0,1]
	ds_write_b128 v193, v[4:7] offset:2048
	ds_read_b128 v[4:7], v193 offset:4096
	s_waitcnt lgkmcnt(2)
	v_pk_fma_f32 v[10:11], v[70:71], v[12:13], v[10:11] op_sel_hi:[1,0,1]
	v_pk_fma_f32 v[8:9], v[66:67], v[12:13], v[8:9] op_sel_hi:[1,0,1]
	ds_write_b128 v193, v[8:11] offset:3072
	ds_read_b128 v[8:11], v193 offset:5120
	s_waitcnt lgkmcnt(2)
	v_pk_fma_f32 v[6:7], v[74:75], v[12:13], v[6:7] op_sel_hi:[1,0,1]
	v_pk_fma_f32 v[4:5], v[68:69], v[12:13], v[4:5] op_sel_hi:[1,0,1]
	ds_write_b128 v193, v[4:7] offset:4096
	ds_read_b128 v[4:7], v193 offset:6144
	s_waitcnt lgkmcnt(2)
	v_pk_fma_f32 v[10:11], v[78:79], v[12:13], v[10:11] op_sel_hi:[1,0,1]
	v_pk_fma_f32 v[8:9], v[72:73], v[12:13], v[8:9] op_sel_hi:[1,0,1]
	ds_write_b128 v193, v[8:11] offset:5120
	ds_read_b128 v[8:11], v193 offset:7168
	s_waitcnt lgkmcnt(2)
	v_pk_fma_f32 v[6:7], v[82:83], v[12:13], v[6:7] op_sel_hi:[1,0,1]
	v_pk_fma_f32 v[4:5], v[76:77], v[12:13], v[4:5] op_sel_hi:[1,0,1]
	ds_write_b128 v193, v[4:7] offset:6144
	v_pk_mul_f32 v[6:7], v[34:35], v[12:13] op_sel_hi:[1,0]
	s_waitcnt lgkmcnt(1)
	v_pk_fma_f32 v[4:5], v[80:81], v[12:13], v[8:9] op_sel_hi:[1,0,1]
	v_pk_add_f32 v[6:7], v[6:7], v[10:11] op_sel:[1,0] op_sel_hi:[0,1]
	ds_write_b128 v193, v[4:7] offset:7168
	s_cbranch_scc0 .LBB0_604
.LBB0_572:
	s_waitcnt vmcnt(0)
	v_mov_b32_e32 v50, v214
	v_mov_b32_e32 v51, v215
	v_mov_b32_e32 v52, v216
	v_mov_b32_e32 v53, v217
	v_mov_b32_e32 v12, v218
	v_mov_b32_e32 v13, v219
	v_mov_b32_e32 v14, v220
	v_mov_b32_e32 v15, v221
	v_mov_b32_e32 v8, v222
	v_mov_b32_e32 v9, v223
	v_mov_b32_e32 v10, v224
	v_mov_b32_e32 v11, v225
	v_mov_b32_e32 v4, v226
	v_mov_b32_e32 v5, v227
	v_mov_b32_e32 v6, v228
	v_mov_b32_e32 v7, v229
	s_cmp_eq_u32 s16, 0x1800000
	s_cbranch_scc1 .Limp_nopf
	s_add_u32 vcc_lo, s16, 0x800000
	s_addc_u32 vcc_hi, s17, 0
	v_lshl_add_u64 v[230:231], v[16:17], 0, vcc
	global_load_dwordx4 v[214:217], v[230:231], off offset:-64
	global_load_dwordx4 v[218:221], v[230:231], off offset:-32
	global_load_dwordx4 v[222:225], v[230:231], off
	global_load_dwordx4 v[226:229], v[230:231], off offset:32
.Limp_nopf:
	v_mov_b32_e32 v59, 0
	s_andn2_b64 vcc, exec, s[80:81]
	v_mov_b32_e32 v58, 0
	v_mov_b32_e32 v55, 0
	v_mov_b32_e32 v54, 0
	v_mov_b32_e32 v3, 0
	v_mov_b32_e32 v56, 0
	s_cbranch_vccnz .LBB0_576
	ds_read_b128 v[54:57], v88
	s_andn2_b64 vcc, exec, s[82:83]
	s_waitcnt lgkmcnt(0)
	v_mfma_f32_32x32x16_bf16 v[34:49], v[54:57], v[50:53], v[18:33]
	ds_read_b128 v[54:57], v89
	s_waitcnt lgkmcnt(0)
	v_mfma_f32_32x32x16_bf16 v[34:49], v[54:57], v[12:15], v[34:49]
	ds_read_b128 v[54:57], v90
	s_waitcnt lgkmcnt(0)
	v_mfma_f32_32x32x16_bf16 v[34:49], v[54:57], v[8:11], v[34:49]
	ds_read_b128 v[54:57], v91
	s_waitcnt lgkmcnt(0)
	v_mfma_f32_32x32x16_bf16 v[34:49], v[54:57], v[4:7], v[34:49]
	s_cbranch_vccnz .LBB0_575
	v_readlane_b32 vcc_lo, v243, 54
	v_readlane_b32 vcc_hi, v243, 55
	s_nop 8
	v_cndmask_b32_e32 v34, v34, v190, vcc
	v_readlane_b32 vcc_lo, v243, 56
	v_readlane_b32 vcc_hi, v243, 57
	s_nop 1
	v_cndmask_b32_e32 v35, v35, v190, vcc
	v_readlane_b32 vcc_lo, v243, 58
	v_readlane_b32 vcc_hi, v243, 59
	s_nop 1
	v_cndmask_b32_e32 v36, v36, v190, vcc
	v_readlane_b32 vcc_lo, v243, 60
	v_readlane_b32 vcc_hi, v243, 61
	s_nop 1
	v_cndmask_b32_e32 v37, v37, v190, vcc
	v_readlane_b32 vcc_lo, v243, 62
	v_readlane_b32 vcc_hi, v243, 63
	s_nop 1
	v_cndmask_b32_e32 v38, v38, v190, vcc
	v_readlane_b32 vcc_lo, v242, 0
	v_readlane_b32 vcc_hi, v242, 1
	s_nop 1
	v_cndmask_b32_e32 v39, v39, v190, vcc
	v_readlane_b32 vcc_lo, v242, 2
	v_readlane_b32 vcc_hi, v242, 3
	s_nop 1
	v_cndmask_b32_e32 v40, v40, v190, vcc
	v_readlane_b32 vcc_lo, v242, 4
	v_readlane_b32 vcc_hi, v242, 5
	s_nop 1
	v_cndmask_b32_e32 v41, v41, v190, vcc
	v_readlane_b32 vcc_lo, v242, 6
	v_readlane_b32 vcc_hi, v242, 7
	s_nop 1
	v_cndmask_b32_e32 v42, v42, v190, vcc
	v_readlane_b32 vcc_lo, v242, 8
	v_readlane_b32 vcc_hi, v242, 9
	s_nop 1
	v_cndmask_b32_e32 v43, v43, v190, vcc
	v_readlane_b32 vcc_lo, v242, 10
	v_readlane_b32 vcc_hi, v242, 11
	s_nop 1
	v_cndmask_b32_e32 v44, v44, v190, vcc
	v_readlane_b32 vcc_lo, v242, 12
	v_readlane_b32 vcc_hi, v242, 13
	s_nop 1
	v_cndmask_b32_e32 v45, v45, v190, vcc
	v_readlane_b32 vcc_lo, v242, 14
	v_readlane_b32 vcc_hi, v242, 15
	s_nop 1
	v_cndmask_b32_e32 v46, v46, v190, vcc
	v_readlane_b32 vcc_lo, v242, 16
	v_readlane_b32 vcc_hi, v242, 17
	s_nop 1
	v_cndmask_b32_e32 v47, v47, v190, vcc
	v_readlane_b32 vcc_lo, v242, 18
	v_readlane_b32 vcc_hi, v242, 19
	s_nop 1
	v_cndmask_b32_e32 v48, v48, v190, vcc
	v_readlane_b32 vcc_lo, v242, 20
	v_readlane_b32 vcc_hi, v242, 21
	s_nop 1
	v_cndmask_b32_e32 v49, v49, v190, vcc

.LBB0_576:
	v_mov_b32_e32 v61, 0
	s_andn2_b64 vcc, exec, s[84:85]
	s_cbranch_vccnz .LBB0_585
	ds_read_b128 v[60:63], v88 offset:4096
	s_andn2_b64 vcc, exec, s[86:87]
	s_waitcnt lgkmcnt(0)
	v_mfma_f32_32x32x16_bf16 v[34:49], v[60:63], v[50:53], v[18:33]
	ds_read_b128 v[60:63], v89 offset:4096
	s_waitcnt lgkmcnt(0)
	v_mfma_f32_32x32x16_bf16 v[34:49], v[60:63], v[12:15], v[34:49]
	ds_read_b128 v[60:63], v90 offset:4096
	s_waitcnt lgkmcnt(0)
	v_mfma_f32_32x32x16_bf16 v[34:49], v[60:63], v[8:11], v[34:49]
	ds_read_b128 v[60:63], v91 offset:4096
	s_waitcnt lgkmcnt(0)
	v_mfma_f32_32x32x16_bf16 v[34:49], v[60:63], v[4:7], v[34:49]
	s_cbranch_vccnz .LBB0_579
	v_readlane_b32 vcc_lo, v242, 22
	v_readlane_b32 vcc_hi, v242, 23
	s_nop 8
	v_cndmask_b32_e32 v34, v34, v190, vcc
	v_readlane_b32 vcc_lo, v242, 24
	v_readlane_b32 vcc_hi, v242, 25
	s_nop 1
	v_cndmask_b32_e32 v35, v35, v190, vcc
	v_readlane_b32 vcc_lo, v242, 26
	v_readlane_b32 vcc_hi, v242, 27
	s_nop 1
	v_cndmask_b32_e32 v36, v36, v190, vcc
	v_readlane_b32 vcc_lo, v242, 28
	v_readlane_b32 vcc_hi, v242, 29
	s_nop 1
	v_cndmask_b32_e32 v37, v37, v190, vcc
	v_readlane_b32 vcc_lo, v242, 30
	v_readlane_b32 vcc_hi, v242, 31
	s_nop 1
	v_cndmask_b32_e32 v38, v38, v190, vcc
	v_readlane_b32 vcc_lo, v242, 32
	v_readlane_b32 vcc_hi, v242, 33
	s_nop 1
	v_cndmask_b32_e32 v39, v39, v190, vcc
	v_readlane_b32 vcc_lo, v242, 34
	v_readlane_b32 vcc_hi, v242, 35
	s_nop 1
	v_cndmask_b32_e32 v40, v40, v190, vcc
	v_readlane_b32 vcc_lo, v242, 36
	v_readlane_b32 vcc_hi, v242, 37
	s_nop 1
	v_cndmask_b32_e32 v41, v41, v190, vcc
	v_readlane_b32 vcc_lo, v242, 38
	v_readlane_b32 vcc_hi, v242, 39
	s_nop 1
	v_cndmask_b32_e32 v42, v42, v190, vcc
	v_readlane_b32 vcc_lo, v242, 42
	v_readlane_b32 vcc_hi, v242, 43
	s_nop 1
	v_cndmask_b32_e32 v43, v43, v190, vcc
	v_readlane_b32 vcc_lo, v242, 44
	v_readlane_b32 vcc_hi, v242, 45
	s_nop 1
	v_cndmask_b32_e32 v44, v44, v190, vcc
	v_readlane_b32 vcc_lo, v242, 46
	v_readlane_b32 vcc_hi, v242, 47
	s_nop 1
	v_cndmask_b32_e32 v45, v45, v190, vcc
	v_readlane_b32 vcc_lo, v242, 48
	v_readlane_b32 vcc_hi, v242, 49
	s_nop 1
	v_cndmask_b32_e32 v46, v46, v190, vcc
	v_readlane_b32 vcc_lo, v242, 50
	v_readlane_b32 vcc_hi, v242, 51
	s_nop 1
	v_cndmask_b32_e32 v47, v47, v190, vcc
	v_readlane_b32 vcc_lo, v242, 52
	v_readlane_b32 vcc_hi, v242, 53
	s_nop 1
	v_cndmask_b32_e32 v48, v48, v190, vcc
	v_readlane_b32 vcc_lo, v242, 54
	v_readlane_b32 vcc_hi, v242, 55
	s_nop 1
	v_cndmask_b32_e32 v49, v49, v190, vcc

.LBB0_586:
	ds_read_b128 v[64:67], v88 offset:8192
	s_andn2_b64 vcc, exec, s[90:91]
	s_waitcnt lgkmcnt(0)
	v_mfma_f32_32x32x16_bf16 v[34:49], v[64:67], v[50:53], v[18:33]
	ds_read_b128 v[64:67], v89 offset:8192
	s_waitcnt lgkmcnt(0)
	v_mfma_f32_32x32x16_bf16 v[34:49], v[64:67], v[12:15], v[34:49]
	ds_read_b128 v[64:67], v90 offset:8192
	s_waitcnt lgkmcnt(0)
	v_mfma_f32_32x32x16_bf16 v[34:49], v[64:67], v[8:11], v[34:49]
	ds_read_b128 v[64:67], v91 offset:8192
	s_waitcnt lgkmcnt(0)
	v_mfma_f32_32x32x16_bf16 v[34:49], v[64:67], v[4:7], v[34:49]
	s_cbranch_vccnz .LBB0_588
	v_readlane_b32 vcc_lo, v242, 56
	v_readlane_b32 vcc_hi, v242, 57
	s_nop 8
	v_cndmask_b32_e32 v34, v34, v190, vcc
	v_readlane_b32 vcc_lo, v242, 58
	v_readlane_b32 vcc_hi, v242, 59
	s_nop 1
	v_cndmask_b32_e32 v35, v35, v190, vcc
	v_readlane_b32 vcc_lo, v242, 60
	v_readlane_b32 vcc_hi, v242, 61
	s_nop 1
	v_cndmask_b32_e32 v36, v36, v190, vcc
	v_readlane_b32 vcc_lo, v242, 62
	v_readlane_b32 vcc_hi, v242, 63
	s_nop 1
	v_cndmask_b32_e32 v37, v37, v190, vcc
	v_readlane_b32 vcc_lo, v241, 0
	v_readlane_b32 vcc_hi, v241, 1
	s_nop 1
	v_cndmask_b32_e32 v38, v38, v190, vcc
	v_readlane_b32 vcc_lo, v241, 2
	v_readlane_b32 vcc_hi, v241, 3
	s_nop 1
	v_cndmask_b32_e32 v39, v39, v190, vcc
	v_readlane_b32 vcc_lo, v241, 4
	v_readlane_b32 vcc_hi, v241, 5
	s_nop 1
	v_cndmask_b32_e32 v40, v40, v190, vcc
	v_readlane_b32 vcc_lo, v241, 6
	v_readlane_b32 vcc_hi, v241, 7
	s_nop 1
	v_cndmask_b32_e32 v41, v41, v190, vcc
	v_readlane_b32 vcc_lo, v241, 8
	v_readlane_b32 vcc_hi, v241, 9
	s_nop 1
	v_cndmask_b32_e32 v42, v42, v190, vcc
	v_readlane_b32 vcc_lo, v241, 10
	v_readlane_b32 vcc_hi, v241, 11
	s_nop 1
	v_cndmask_b32_e32 v43, v43, v190, vcc
	v_readlane_b32 vcc_lo, v241, 12
	v_readlane_b32 vcc_hi, v241, 13
	s_nop 1
	v_cndmask_b32_e32 v44, v44, v190, vcc
	v_readlane_b32 vcc_lo, v241, 14
	v_readlane_b32 vcc_hi, v241, 15
	s_nop 1
	v_cndmask_b32_e32 v45, v45, v190, vcc
	v_readlane_b32 vcc_lo, v241, 16
	v_readlane_b32 vcc_hi, v241, 17
	s_nop 1
	v_cndmask_b32_e32 v46, v46, v190, vcc
	v_readlane_b32 vcc_lo, v241, 18
	v_readlane_b32 vcc_hi, v241, 19
	s_nop 1
	v_cndmask_b32_e32 v47, v47, v190, vcc
	v_readlane_b32 vcc_lo, v241, 20
	v_readlane_b32 vcc_hi, v241, 21
	s_nop 1
	v_cndmask_b32_e32 v48, v48, v190, vcc
	v_readlane_b32 vcc_lo, v241, 22
	v_readlane_b32 vcc_hi, v241, 23
	s_nop 1
	v_cndmask_b32_e32 v49, v49, v190, vcc

.LBB0_589:
	ds_read_b128 v[68:71], v88 offset:12288
	s_andn2_b64 vcc, exec, s[94:95]
	s_waitcnt lgkmcnt(0)
	v_mfma_f32_32x32x16_bf16 v[34:49], v[68:71], v[50:53], v[18:33]
	ds_read_b128 v[68:71], v89 offset:12288
	s_waitcnt lgkmcnt(0)
	v_mfma_f32_32x32x16_bf16 v[34:49], v[68:71], v[12:15], v[34:49]
	ds_read_b128 v[68:71], v90 offset:12288
	s_waitcnt lgkmcnt(0)
	v_mfma_f32_32x32x16_bf16 v[34:49], v[68:71], v[8:11], v[34:49]
	ds_read_b128 v[68:71], v91 offset:12288
	s_waitcnt lgkmcnt(0)
	v_mfma_f32_32x32x16_bf16 v[34:49], v[68:71], v[4:7], v[34:49]
	s_cbranch_vccnz .LBB0_591
	v_readlane_b32 vcc_lo, v241, 24
	v_readlane_b32 vcc_hi, v241, 25
	s_nop 8
	v_cndmask_b32_e32 v34, v34, v190, vcc
	v_readlane_b32 vcc_lo, v241, 26
	v_readlane_b32 vcc_hi, v241, 27
	s_nop 1
	v_cndmask_b32_e32 v35, v35, v190, vcc
	v_readlane_b32 vcc_lo, v241, 28
	v_readlane_b32 vcc_hi, v241, 29
	s_nop 1
	v_cndmask_b32_e32 v36, v36, v190, vcc
	v_readlane_b32 vcc_lo, v241, 30
	v_readlane_b32 vcc_hi, v241, 31
	s_nop 1
	v_cndmask_b32_e32 v37, v37, v190, vcc
	v_readlane_b32 vcc_lo, v241, 32
	v_readlane_b32 vcc_hi, v241, 33
	s_nop 1
	v_cndmask_b32_e32 v38, v38, v190, vcc
	v_readlane_b32 vcc_lo, v241, 34
	v_readlane_b32 vcc_hi, v241, 35
	s_nop 1
	v_cndmask_b32_e32 v39, v39, v190, vcc
	v_readlane_b32 vcc_lo, v241, 36
	v_readlane_b32 vcc_hi, v241, 37
	s_nop 1
	v_cndmask_b32_e32 v40, v40, v190, vcc
	v_readlane_b32 vcc_lo, v241, 38
	v_readlane_b32 vcc_hi, v241, 39
	s_nop 1
	v_cndmask_b32_e32 v41, v41, v190, vcc
	v_readlane_b32 vcc_lo, v241, 40
	v_readlane_b32 vcc_hi, v241, 41
	s_nop 1
	v_cndmask_b32_e32 v42, v42, v190, vcc
	v_readlane_b32 vcc_lo, v241, 42
	v_readlane_b32 vcc_hi, v241, 43
	s_nop 1
	v_cndmask_b32_e32 v43, v43, v190, vcc
	v_readlane_b32 vcc_lo, v241, 44
	v_readlane_b32 vcc_hi, v241, 45
	s_nop 1
	v_cndmask_b32_e32 v44, v44, v190, vcc
	v_readlane_b32 vcc_lo, v241, 46
	v_readlane_b32 vcc_hi, v241, 47
	s_nop 1
	v_cndmask_b32_e32 v45, v45, v190, vcc
	v_readlane_b32 vcc_lo, v241, 48
	v_readlane_b32 vcc_hi, v241, 49
	s_nop 1
	v_cndmask_b32_e32 v46, v46, v190, vcc
	v_readlane_b32 vcc_lo, v241, 50
	v_readlane_b32 vcc_hi, v241, 51
	s_nop 1
	v_cndmask_b32_e32 v47, v47, v190, vcc
	v_readlane_b32 vcc_lo, v241, 52
	v_readlane_b32 vcc_hi, v241, 53
	s_nop 1
	v_cndmask_b32_e32 v48, v48, v190, vcc
	v_readlane_b32 vcc_lo, v241, 54
	v_readlane_b32 vcc_hi, v241, 55
	s_nop 1
	v_cndmask_b32_e32 v49, v49, v190, vcc

.LBB0_592:
	ds_read_b128 v[72:75], v88 offset:16384
	s_andn2_b64 vcc, exec, s[98:99]
	s_waitcnt lgkmcnt(0)
	v_mfma_f32_32x32x16_bf16 v[34:49], v[72:75], v[50:53], v[18:33]
	ds_read_b128 v[72:75], v89 offset:16384
	s_waitcnt lgkmcnt(0)
	v_mfma_f32_32x32x16_bf16 v[34:49], v[72:75], v[12:15], v[34:49]
	ds_read_b128 v[72:75], v90 offset:16384
	s_waitcnt lgkmcnt(0)
	v_mfma_f32_32x32x16_bf16 v[34:49], v[72:75], v[8:11], v[34:49]
	ds_read_b128 v[72:75], v91 offset:16384
	s_waitcnt lgkmcnt(0)
	v_mfma_f32_32x32x16_bf16 v[34:49], v[72:75], v[4:7], v[34:49]
	s_cbranch_vccnz .LBB0_594
	v_readlane_b32 vcc_lo, v241, 56
	v_readlane_b32 vcc_hi, v241, 57
	s_nop 8
	v_cndmask_b32_e32 v34, v34, v190, vcc
	v_readlane_b32 vcc_lo, v241, 58
	v_readlane_b32 vcc_hi, v241, 59
	s_nop 1
	v_cndmask_b32_e32 v35, v35, v190, vcc
	v_readlane_b32 vcc_lo, v241, 60
	v_readlane_b32 vcc_hi, v241, 61
	s_nop 1
	v_cndmask_b32_e32 v36, v36, v190, vcc
	v_readlane_b32 vcc_lo, v241, 62
	v_readlane_b32 vcc_hi, v241, 63
	s_nop 1
	v_cndmask_b32_e32 v37, v37, v190, vcc
	v_readlane_b32 vcc_lo, v240, 0
	v_readlane_b32 vcc_hi, v240, 1
	s_nop 1
	v_cndmask_b32_e32 v38, v38, v190, vcc
	v_readlane_b32 vcc_lo, v240, 2
	v_readlane_b32 vcc_hi, v240, 3
	s_nop 1
	v_cndmask_b32_e32 v39, v39, v190, vcc
	v_readlane_b32 vcc_lo, v240, 4
	v_readlane_b32 vcc_hi, v240, 5
	s_nop 1
	v_cndmask_b32_e32 v40, v40, v190, vcc
	v_readlane_b32 vcc_lo, v240, 6
	v_readlane_b32 vcc_hi, v240, 7
	s_nop 1
	v_cndmask_b32_e32 v41, v41, v190, vcc
	v_readlane_b32 vcc_lo, v240, 8
	v_readlane_b32 vcc_hi, v240, 9
	s_nop 1
	v_cndmask_b32_e32 v42, v42, v190, vcc
	v_readlane_b32 vcc_lo, v240, 10
	v_readlane_b32 vcc_hi, v240, 11
	s_nop 1
	v_cndmask_b32_e32 v43, v43, v190, vcc
	v_readlane_b32 vcc_lo, v240, 12
	v_readlane_b32 vcc_hi, v240, 13
	s_nop 1
	v_cndmask_b32_e32 v44, v44, v190, vcc
	v_readlane_b32 vcc_lo, v240, 14
	v_readlane_b32 vcc_hi, v240, 15
	s_nop 1
	v_cndmask_b32_e32 v45, v45, v190, vcc
	v_readlane_b32 vcc_lo, v240, 16
	v_readlane_b32 vcc_hi, v240, 17
	s_nop 1
	v_cndmask_b32_e32 v46, v46, v190, vcc
	v_readlane_b32 vcc_lo, v240, 18
	v_readlane_b32 vcc_hi, v240, 19
	s_nop 1
	v_cndmask_b32_e32 v47, v47, v190, vcc
	v_readlane_b32 vcc_lo, v240, 20
	v_readlane_b32 vcc_hi, v240, 21
	s_nop 1
	v_cndmask_b32_e32 v48, v48, v190, vcc
	v_readlane_b32 vcc_lo, v240, 22
	v_readlane_b32 vcc_hi, v240, 23
	s_nop 1
	v_cndmask_b32_e32 v49, v49, v190, vcc

.LBB0_595:
	ds_read_b128 v[76:79], v88 offset:20480
	s_andn2_b64 vcc, exec, s[8:9]
	s_waitcnt lgkmcnt(0)
	v_mfma_f32_32x32x16_bf16 v[34:49], v[76:79], v[50:53], v[18:33]
	ds_read_b128 v[76:79], v89 offset:20480
	s_waitcnt lgkmcnt(0)
	v_mfma_f32_32x32x16_bf16 v[34:49], v[76:79], v[12:15], v[34:49]
	ds_read_b128 v[76:79], v90 offset:20480
	s_waitcnt lgkmcnt(0)
	v_mfma_f32_32x32x16_bf16 v[34:49], v[76:79], v[8:11], v[34:49]
	ds_read_b128 v[76:79], v91 offset:20480
	s_waitcnt lgkmcnt(0)
	v_mfma_f32_32x32x16_bf16 v[34:49], v[76:79], v[4:7], v[34:49]
	s_cbranch_vccnz .LBB0_597
	v_readlane_b32 vcc_lo, v240, 24
	v_readlane_b32 vcc_hi, v240, 25
	s_nop 8
	v_cndmask_b32_e32 v34, v34, v190, vcc
	v_readlane_b32 vcc_lo, v240, 26
	v_readlane_b32 vcc_hi, v240, 27
	s_nop 1
	v_cndmask_b32_e32 v35, v35, v190, vcc
	v_readlane_b32 vcc_lo, v240, 28
	v_readlane_b32 vcc_hi, v240, 29
	s_nop 1
	v_cndmask_b32_e32 v36, v36, v190, vcc
	v_readlane_b32 vcc_lo, v240, 30
	v_readlane_b32 vcc_hi, v240, 31
	s_nop 1
	v_cndmask_b32_e32 v37, v37, v190, vcc
	v_readlane_b32 vcc_lo, v240, 32
	v_readlane_b32 vcc_hi, v240, 33
	s_nop 1
	v_cndmask_b32_e32 v38, v38, v190, vcc
	v_readlane_b32 vcc_lo, v240, 34
	v_readlane_b32 vcc_hi, v240, 35
	s_nop 1
	v_cndmask_b32_e32 v39, v39, v190, vcc
	v_readlane_b32 vcc_lo, v240, 36
	v_readlane_b32 vcc_hi, v240, 37
	s_nop 1
	v_cndmask_b32_e32 v40, v40, v190, vcc
	v_readlane_b32 vcc_lo, v240, 38
	v_readlane_b32 vcc_hi, v240, 39
	s_nop 1
	v_cndmask_b32_e32 v41, v41, v190, vcc
	v_readlane_b32 vcc_lo, v240, 40
	v_readlane_b32 vcc_hi, v240, 41
	s_nop 1
	v_cndmask_b32_e32 v42, v42, v190, vcc
	v_readlane_b32 vcc_lo, v240, 42
	v_readlane_b32 vcc_hi, v240, 43
	s_nop 1
	v_cndmask_b32_e32 v43, v43, v190, vcc
	v_readlane_b32 vcc_lo, v240, 44
	v_readlane_b32 vcc_hi, v240, 45
	s_nop 1
	v_cndmask_b32_e32 v44, v44, v190, vcc
	v_readlane_b32 vcc_lo, v240, 46
	v_readlane_b32 vcc_hi, v240, 47
	s_nop 1
	v_cndmask_b32_e32 v45, v45, v190, vcc
	v_readlane_b32 vcc_lo, v240, 48
	v_readlane_b32 vcc_hi, v240, 49
	s_nop 1
	v_cndmask_b32_e32 v46, v46, v190, vcc
	v_readlane_b32 vcc_lo, v240, 50
	v_readlane_b32 vcc_hi, v240, 51
	s_nop 1
	v_cndmask_b32_e32 v47, v47, v190, vcc
	v_readlane_b32 vcc_lo, v240, 52
	v_readlane_b32 vcc_hi, v240, 53
	s_nop 1
	v_cndmask_b32_e32 v48, v48, v190, vcc
	v_readlane_b32 vcc_lo, v240, 54
	v_readlane_b32 vcc_hi, v240, 55
	s_nop 1
	v_cndmask_b32_e32 v49, v49, v190, vcc

.LBB0_598:
	ds_read_b128 v[80:83], v88 offset:24576
	s_andn2_b64 vcc, exec, s[10:11]
	s_waitcnt lgkmcnt(0)
	v_mfma_f32_32x32x16_bf16 v[34:49], v[80:83], v[50:53], v[18:33]
	ds_read_b128 v[80:83], v89 offset:24576
	s_waitcnt lgkmcnt(0)
	v_mfma_f32_32x32x16_bf16 v[34:49], v[80:83], v[12:15], v[34:49]
	ds_read_b128 v[80:83], v90 offset:24576
	s_waitcnt lgkmcnt(0)
	v_mfma_f32_32x32x16_bf16 v[34:49], v[80:83], v[8:11], v[34:49]
	ds_read_b128 v[80:83], v91 offset:24576
	s_waitcnt lgkmcnt(0)
	v_mfma_f32_32x32x16_bf16 v[34:49], v[80:83], v[4:7], v[34:49]
	s_cbranch_vccnz .LBB0_600
	v_readlane_b32 vcc_lo, v240, 56
	v_readlane_b32 vcc_hi, v240, 57
	s_nop 8
	v_cndmask_b32_e64 v37, v37, v190, s[18:19]
	v_cndmask_b32_e64 v38, v38, v190, s[20:21]
	v_cndmask_b32_e32 v34, v34, v190, vcc
	v_readlane_b32 vcc_lo, v240, 58
	v_readlane_b32 vcc_hi, v240, 59
	v_cndmask_b32_e64 v39, v39, v190, s[22:23]
	v_cndmask_b32_e64 v40, v40, v190, s[24:25]
	v_cndmask_b32_e32 v35, v35, v190, vcc
	v_readlane_b32 vcc_lo, v240, 60
	v_readlane_b32 vcc_hi, v240, 61
	v_cndmask_b32_e64 v41, v41, v190, s[26:27]
	v_cndmask_b32_e64 v42, v42, v190, s[28:29]
	v_cndmask_b32_e32 v36, v36, v190, vcc
	v_cndmask_b32_e64 v43, v43, v190, s[30:31]
	v_cndmask_b32_e64 v44, v44, v190, s[34:35]
	v_cndmask_b32_e64 v45, v45, v190, s[36:37]
	v_cndmask_b32_e64 v46, v46, v190, s[38:39]
	v_cndmask_b32_e64 v47, v47, v190, s[40:41]
	v_cndmask_b32_e64 v48, v48, v190, s[42:43]
	v_cndmask_b32_e64 v49, v49, v190, s[44:45]

.LBB0_601:
	ds_read_b128 v[92:95], v88 offset:28672
	s_andn2_b64 vcc, exec, s[14:15]
	s_waitcnt lgkmcnt(0)
	v_mfma_f32_32x32x16_bf16 v[34:49], v[92:95], v[50:53], v[18:33]
	ds_read_b128 v[50:53], v89 offset:28672
	s_waitcnt lgkmcnt(0)
	v_mfma_f32_32x32x16_bf16 v[34:49], v[50:53], v[12:15], v[34:49]
	ds_read_b128 v[12:15], v90 offset:28672
	s_waitcnt lgkmcnt(0)
	v_mfma_f32_32x32x16_bf16 v[34:49], v[12:15], v[8:11], v[34:49]
	ds_read_b128 v[8:11], v91 offset:28672
	s_waitcnt lgkmcnt(0)
	v_mfma_f32_32x32x16_bf16 v[34:49], v[8:11], v[4:7], v[34:49]
	s_cbranch_vccnz .LBB0_603
	s_nop 10
	v_cndmask_b32_e64 v34, v34, v190, s[46:47]
	v_cndmask_b32_e64 v35, v35, v190, s[48:49]
	v_cndmask_b32_e64 v36, v36, v190, s[50:51]
	v_cndmask_b32_e64 v37, v37, v190, s[52:53]
	v_cndmask_b32_e64 v38, v38, v190, s[54:55]
	v_cndmask_b32_e64 v39, v39, v190, s[56:57]
	v_cndmask_b32_e64 v40, v40, v190, s[58:59]
	v_cndmask_b32_e64 v41, v41, v190, s[60:61]
	v_cndmask_b32_e64 v42, v42, v190, s[62:63]
	v_cndmask_b32_e64 v43, v43, v190, s[64:65]
	v_cndmask_b32_e64 v44, v44, v190, s[66:67]
	v_cndmask_b32_e64 v45, v45, v190, s[68:69]
	v_cndmask_b32_e64 v46, v46, v190, s[70:71]
	v_cndmask_b32_e64 v47, v47, v190, s[72:73]
	v_cndmask_b32_e64 v48, v48, v190, s[74:75]
	v_cndmask_b32_e64 v49, v49, v190, s[76:77]
